# F4 variant: invalidate issued after the arrival atomic has returned (not before it)
# speedup vs baseline: 1.0312x; 1.0014x over previous
.LBB1_179:
	v_readlane_b32 s6, v254, 21
	v_readlane_b32 s7, v254, 22
	v_cvt_f32_u32_e32 v1, v2
	v_sub_u32_e32 v4, 0, v2
	v_rcp_iflag_f32_e32 v1, v1
	s_nop 1
	global_atomic_add v3, v113, v215, s[6:7] sc0
	v_mul_f32_e32 v1, 0x4f7ffffe, v1
	v_cvt_u32_f32_e32 v1, v1
	v_mul_lo_u32 v4, v4, v1
	v_mul_hi_u32 v4, v1, v4
	v_add_u32_e32 v1, v1, v4
	s_waitcnt vmcnt(0)
	buffer_inv sc1
	v_mul_hi_u32 v1, v3, v1
	v_mul_lo_u32 v4, v1, v2
	v_sub_u32_e32 v4, v3, v4
	v_add_u32_e32 v5, 1, v1
	v_cmp_ge_u32_e32 vcc, v4, v2
	v_add_u32_e32 v3, 1, v3
	s_nop 0
	v_cndmask_b32_e32 v1, v1, v5, vcc
	v_sub_u32_e32 v5, v4, v2
	v_cndmask_b32_e32 v4, v4, v5, vcc
	v_add_u32_e32 v5, 1, v1
	v_cmp_ge_u32_e32 vcc, v4, v2
	s_nop 1
	v_cndmask_b32_e32 v1, v1, v5, vcc
	v_mul_lo_u32 v4, v2, v1
	v_add_u32_e32 v2, v4, v2
	v_cmp_ne_u32_e32 vcc, v3, v2
	s_and_saveexec_b64 s[6:7], vcc
	s_xor_b64 s[16:17], exec, s[6:7]
	s_cbranch_execz .LBB1_193
	v_readlane_b32 s6, v254, 27
	v_readlane_b32 s7, v254, 28
	s_waitcnt lgkmcnt(0)
	s_nop 3
	global_load_dword v0, v113, s[6:7] sc1
	s_waitcnt vmcnt(0)
	v_cmp_eq_u32_e32 vcc, v0, v1
	s_and_saveexec_b64 s[18:19], vcc
	s_cbranch_execz .LBB1_192
	s_mov_b32 s5, 1
	s_mov_b64 s[26:27], 0
	s_branch .LBB1_183

.LBB1_312:
	v_readlane_b32 s6, v254, 21
	v_readlane_b32 s7, v254, 22
	v_cvt_f32_u32_e32 v1, v2
	v_sub_u32_e32 v4, 0, v2
	v_rcp_iflag_f32_e32 v1, v1
	s_nop 1
	global_atomic_add v3, v113, v215, s[6:7] sc0
	v_mul_f32_e32 v1, 0x4f7ffffe, v1
	v_cvt_u32_f32_e32 v1, v1
	v_mul_lo_u32 v4, v4, v1
	v_mul_hi_u32 v4, v1, v4
	v_add_u32_e32 v1, v1, v4
	s_waitcnt vmcnt(0)
	buffer_inv sc1
	v_mul_hi_u32 v1, v3, v1
	v_mul_lo_u32 v4, v1, v2
	v_sub_u32_e32 v4, v3, v4
	v_add_u32_e32 v5, 1, v1
	v_cmp_ge_u32_e32 vcc, v4, v2
	v_add_u32_e32 v3, 1, v3
	s_nop 0
	v_cndmask_b32_e32 v1, v1, v5, vcc
	v_sub_u32_e32 v5, v4, v2
	v_cndmask_b32_e32 v4, v4, v5, vcc
	v_add_u32_e32 v5, 1, v1
	v_cmp_ge_u32_e32 vcc, v4, v2
	s_nop 1
	v_cndmask_b32_e32 v1, v1, v5, vcc
	v_mul_lo_u32 v4, v2, v1
	v_add_u32_e32 v2, v4, v2
	v_cmp_ne_u32_e32 vcc, v3, v2
	s_and_saveexec_b64 s[6:7], vcc
	s_xor_b64 s[18:19], exec, s[6:7]
	s_cbranch_execz .LBB1_326
	v_readlane_b32 s6, v254, 27
	v_readlane_b32 s7, v254, 28
	s_waitcnt lgkmcnt(0)
	s_nop 3
	global_load_dword v0, v113, s[6:7] sc1
	s_waitcnt vmcnt(0)
	v_cmp_eq_u32_e32 vcc, v0, v1
	s_and_saveexec_b64 s[26:27], vcc
	s_cbranch_execz .LBB1_325
	s_mov_b32 s5, 1
	s_mov_b64 s[30:31], 0
	s_branch .LBB1_316

.LBB1_1285:
	v_readlane_b32 s6, v254, 21
	v_readlane_b32 s7, v254, 22
	v_cvt_f32_u32_e32 v1, v2
	v_sub_u32_e32 v4, 0, v2
	v_rcp_iflag_f32_e32 v1, v1
	s_nop 1
	global_atomic_add v3, v113, v215, s[6:7] sc0
	v_mul_f32_e32 v1, 0x4f7ffffe, v1
	v_cvt_u32_f32_e32 v1, v1
	v_mul_lo_u32 v4, v4, v1
	v_mul_hi_u32 v4, v1, v4
	v_add_u32_e32 v1, v1, v4
	s_waitcnt vmcnt(0)
	buffer_inv sc1
	v_mul_hi_u32 v1, v3, v1
	v_mul_lo_u32 v4, v1, v2
	v_sub_u32_e32 v4, v3, v4
	v_add_u32_e32 v5, 1, v1
	v_cmp_ge_u32_e32 vcc, v4, v2
	v_add_u32_e32 v3, 1, v3
	s_nop 0
	v_cndmask_b32_e32 v1, v1, v5, vcc
	v_sub_u32_e32 v5, v4, v2
	v_cndmask_b32_e32 v4, v4, v5, vcc
	v_add_u32_e32 v5, 1, v1
	v_cmp_ge_u32_e32 vcc, v4, v2
	s_nop 1
	v_cndmask_b32_e32 v1, v1, v5, vcc
	v_mul_lo_u32 v4, v2, v1
	v_add_u32_e32 v2, v4, v2
	v_cmp_ne_u32_e32 vcc, v3, v2
	s_and_saveexec_b64 s[6:7], vcc
	s_xor_b64 s[16:17], exec, s[6:7]
	s_cbranch_execz .LBB1_1299
	v_readlane_b32 s6, v254, 27
	v_readlane_b32 s7, v254, 28
	s_waitcnt lgkmcnt(0)
	s_nop 3
	global_load_dword v0, v113, s[6:7] sc1
	s_waitcnt vmcnt(0)
	v_cmp_eq_u32_e32 vcc, v0, v1
	s_and_saveexec_b64 s[18:19], vcc
	s_cbranch_execz .LBB1_1298
	s_mov_b32 s1, 1
	s_mov_b64 s[26:27], 0
	s_branch .LBB1_1289
